# standalone first row-norm phase: 8-row loop unrolled, gain vector loaded once instead of reloaded 4x per row behind vmcnt(0), 7 rows of loads in flight with counted waits
# speedup vs baseline: 1.0038x; 1.0002x over previous
.LBB0_226:
	global_load_dwordx4 v[96:99], v[36:37], off
	global_load_dwordx4 v[100:103], v[36:37], off offset:1024
	global_load_dwordx4 v[104:107], v[36:37], off offset:2048
	global_load_dwordx4 v[108:111], v[36:37], off offset:3072
	global_load_dwordx4 v[112:115], v[44:45], off offset:-2048
	global_load_dwordx4 v[116:119], v[44:45], off offset:-1024
	global_load_dwordx4 v[120:123], v[44:45], off
	global_load_dwordx4 v[124:127], v[44:45], off offset:1024
	v_lshl_add_u64 v[44:45], v[44:45], 0, s[4:5]
	global_load_dwordx4 v[128:131], v[44:45], off offset:-2048
	global_load_dwordx4 v[132:135], v[44:45], off offset:-1024
	global_load_dwordx4 v[136:139], v[44:45], off
	global_load_dwordx4 v[140:143], v[44:45], off offset:1024
	v_lshl_add_u64 v[44:45], v[44:45], 0, s[4:5]
	global_load_dwordx4 v[144:147], v[44:45], off offset:-2048
	global_load_dwordx4 v[148:151], v[44:45], off offset:-1024
	global_load_dwordx4 v[152:155], v[44:45], off
	global_load_dwordx4 v[156:159], v[44:45], off offset:1024
	v_lshl_add_u64 v[44:45], v[44:45], 0, s[4:5]
	global_load_dwordx4 v[160:163], v[44:45], off offset:-2048
	global_load_dwordx4 v[164:167], v[44:45], off offset:-1024
	global_load_dwordx4 v[168:171], v[44:45], off
	global_load_dwordx4 v[172:175], v[44:45], off offset:1024
	v_lshl_add_u64 v[44:45], v[44:45], 0, s[4:5]
	global_load_dwordx4 v[176:179], v[44:45], off offset:-2048
	global_load_dwordx4 v[180:183], v[44:45], off offset:-1024
	global_load_dwordx4 v[184:187], v[44:45], off
	global_load_dwordx4 v[188:191], v[44:45], off offset:1024
	v_lshl_add_u64 v[44:45], v[44:45], 0, s[4:5]
	global_load_dwordx4 v[210:213], v[44:45], off offset:-2048
	global_load_dwordx4 v[214:217], v[44:45], off offset:-1024
	global_load_dwordx4 v[218:221], v[44:45], off
	global_load_dwordx4 v[222:225], v[44:45], off offset:1024
	v_lshl_add_u64 v[44:45], v[44:45], 0, s[4:5]
	global_load_dwordx4 v[226:229], v[44:45], off offset:-2048
	global_load_dwordx4 v[230:233], v[44:45], off offset:-1024
	global_load_dwordx4 v[234:237], v[44:45], off
	global_load_dwordx4 v[238:241], v[44:45], off offset:1024
	v_lshl_add_u64 v[44:45], v[44:45], 0, s[4:5]
	s_waitcnt vmcnt(24)
	v_lshl_add_u64 v[76:77], v[42:43], 0, s[6:7]
	v_add_co_u32_e64 v76, s[0:1], s10, v76
	s_add_u32 s6, s6, 0x800
	s_nop 0
	v_addc_co_u32_e64 v77, s[0:1], 0, v77, s[0:1]
	s_addc_u32 s7, s7, 0
	v_pk_mul_f32 v[78:79], v[114:115], v[114:115]
	v_pk_mul_f32 v[80:81], v[112:113], v[112:113]
	v_pk_mul_f32 v[82:83], v[118:119], v[118:119]
	v_pk_mul_f32 v[84:85], v[116:117], v[116:117]
	v_pk_mov_b32 v[90:91], v[80:81], v[78:79] op_sel:[1,0]
	v_mov_b32_e32 v81, v79
	v_pk_mov_b32 v[78:79], v[84:85], v[82:83] op_sel:[1,0]
	v_mov_b32_e32 v85, v83
	v_mul_f32_e32 v89, v124, v124
	v_mul_f32_e32 v86, v121, v121
	v_mul_f32_e32 v88, v123, v123
	v_pk_add_f32 v[80:81], v[90:91], v[80:81]
	v_pk_add_f32 v[78:79], v[78:79], v[84:85]
	v_mul_f32_e32 v92, v125, v125
	v_mul_f32_e32 v93, v126, v126
	v_mul_f32_e32 v94, v127, v127
	v_pk_fma_f32 v[82:83], v[120:121], v[120:121], v[86:87] op_sel_hi:[1,1,0]
	v_pk_fma_f32 v[86:87], v[122:123], v[122:123], v[88:89] op_sel_hi:[1,1,0]
	v_pk_add_f32 v[80:81], v[80:81], v[80:81] op_sel:[0,1] op_sel_hi:[1,0]
	v_pk_add_f32 v[78:79], v[78:79], v[78:79] op_sel:[0,1] op_sel_hi:[1,0]
	v_mov_b32_e32 v83, v93
	v_mov_b32_e32 v87, v94
	v_mov_b32_e32 v81, v89
	v_mov_b32_e32 v79, v92
	v_pk_add_f32 v[82:83], v[82:83], v[86:87]
	v_pk_add_f32 v[78:79], v[80:81], v[78:79]
	s_nop 0
	v_pk_add_f32 v[78:79], v[78:79], v[82:83]
	s_nop 0
	v_add_f32_e32 v78, v78, v79
	s_waitcnt lgkmcnt(0)
	s_nop 1
	v_add_f32_dpp v78, v78, v78 quad_perm:[1,0,3,2] row_mask:0xf bank_mask:0xf
	s_nop 1
	v_add_f32_dpp v78, v78, v78 quad_perm:[2,3,0,1] row_mask:0xf bank_mask:0xf
	s_nop 1
	v_add_f32_dpp v78, v78, v78 row_half_mirror row_mask:0xf bank_mask:0xf
	s_nop 1
	v_add_f32_dpp v78, v78, v78 row_mirror row_mask:0xf bank_mask:0xf
	ds_bpermute_b32 v79, v51, v78
	s_waitcnt lgkmcnt(0)
	v_add_f32_e32 v78, v78, v79
	v_mov_b32_e32 v79, v78
	s_nop 1
	v_permlane32_swap_b32_e32 v79, v78
	v_add_f32_e32 v78, v78, v79
	v_fmamk_f32 v78, v78, 0x3a800000, v55
	v_mul_f32_e32 v79, 0x4b800000, v78
	v_cmp_gt_f32_e64 s[0:1], s9, v78
	s_nop 1
	v_cndmask_b32_e64 v78, v78, v79, s[0:1]
	v_rsq_f32_e32 v78, v78
	s_nop 0
	v_mul_f32_e32 v79, 0x45800000, v78
	v_cndmask_b32_e64 v78, v78, v79, s[0:1]
	v_pk_mul_f32 v[114:115], v[114:115], v[78:79] op_sel_hi:[1,0]
	v_pk_mul_f32 v[112:113], v[112:113], v[78:79] op_sel_hi:[1,0]
	v_pk_mul_f32 v[114:115], v[98:99], v[114:115]
	v_pk_mul_f32 v[112:113], v[96:97], v[112:113]
	v_pk_fma_f32 v[114:115], v[10:11], v[114:115], v[2:3]
	v_pk_fma_f32 v[112:113], v[8:9], v[112:113], v[0:1]
	v_pk_mul_f32 v[118:119], v[118:119], v[78:79] op_sel_hi:[1,0]
	v_cvt_pk_bf16_f32 v112, v112, v113
	v_cvt_pk_bf16_f32 v113, v114, v115
	global_store_dwordx2 v[76:77], v[112:113], off
	v_pk_mul_f32 v[116:117], v[116:117], v[78:79] op_sel_hi:[1,0]
	v_pk_mul_f32 v[114:115], v[102:103], v[118:119]
	v_pk_mul_f32 v[112:113], v[100:101], v[116:117]
	v_pk_fma_f32 v[114:115], v[14:15], v[114:115], v[6:7]
	v_pk_fma_f32 v[112:113], v[12:13], v[112:113], v[4:5]
	v_pk_mul_f32 v[116:117], v[122:123], v[78:79] op_sel_hi:[1,0]
	v_cvt_pk_bf16_f32 v112, v112, v113
	v_cvt_pk_bf16_f32 v113, v114, v115
	global_store_dwordx2 v[76:77], v[112:113], off offset:512
	v_pk_mul_f32 v[118:119], v[120:121], v[78:79] op_sel_hi:[1,0]
	v_pk_mul_f32 v[114:115], v[106:107], v[116:117]
	v_pk_mul_f32 v[112:113], v[104:105], v[118:119]
	v_pk_fma_f32 v[114:115], v[26:27], v[114:115], v[18:19]
	v_pk_fma_f32 v[112:113], v[24:25], v[112:113], v[16:17]
	v_pk_mul_f32 v[116:117], v[126:127], v[78:79] op_sel_hi:[1,0]
	v_cvt_pk_bf16_f32 v112, v112, v113
	v_cvt_pk_bf16_f32 v113, v114, v115
	global_store_dwordx2 v[76:77], v[112:113], off offset:1024
	v_pk_mul_f32 v[118:119], v[124:125], v[78:79] op_sel_hi:[1,0]
	v_pk_mul_f32 v[114:115], v[110:111], v[116:117]
	v_pk_mul_f32 v[112:113], v[108:109], v[118:119]
	v_pk_fma_f32 v[114:115], v[30:31], v[114:115], v[22:23]
	v_pk_fma_f32 v[112:113], v[28:29], v[112:113], v[20:21]
	s_nop 0
	v_cvt_pk_bf16_f32 v112, v112, v113
	v_cvt_pk_bf16_f32 v113, v114, v115
	global_store_dwordx2 v[76:77], v[112:113], off offset:1536
	global_load_dwordx4 v[112:115], v[44:45], off offset:-2048
	global_load_dwordx4 v[116:119], v[44:45], off offset:-1024
	global_load_dwordx4 v[120:123], v[44:45], off
	global_load_dwordx4 v[124:127], v[44:45], off offset:1024
	v_lshl_add_u64 v[44:45], v[44:45], 0, s[4:5]
	s_waitcnt vmcnt(28)
	v_lshl_add_u64 v[76:77], v[42:43], 0, s[6:7]
	v_add_co_u32_e64 v76, s[0:1], s10, v76
	s_add_u32 s6, s6, 0x800
	s_nop 0
	v_addc_co_u32_e64 v77, s[0:1], 0, v77, s[0:1]
	s_addc_u32 s7, s7, 0
	v_pk_mul_f32 v[78:79], v[130:131], v[130:131]
	v_pk_mul_f32 v[80:81], v[128:129], v[128:129]
	v_pk_mul_f32 v[82:83], v[134:135], v[134:135]
	v_pk_mul_f32 v[84:85], v[132:133], v[132:133]
	v_pk_mov_b32 v[90:91], v[80:81], v[78:79] op_sel:[1,0]
	v_mov_b32_e32 v81, v79
	v_pk_mov_b32 v[78:79], v[84:85], v[82:83] op_sel:[1,0]
	v_mov_b32_e32 v85, v83
	v_mul_f32_e32 v89, v140, v140
	v_mul_f32_e32 v86, v137, v137
	v_mul_f32_e32 v88, v139, v139
	v_pk_add_f32 v[80:81], v[90:91], v[80:81]
	v_pk_add_f32 v[78:79], v[78:79], v[84:85]
	v_mul_f32_e32 v92, v141, v141
	v_mul_f32_e32 v93, v142, v142
	v_mul_f32_e32 v94, v143, v143
	v_pk_fma_f32 v[82:83], v[136:137], v[136:137], v[86:87] op_sel_hi:[1,1,0]
	v_pk_fma_f32 v[86:87], v[138:139], v[138:139], v[88:89] op_sel_hi:[1,1,0]
	v_pk_add_f32 v[80:81], v[80:81], v[80:81] op_sel:[0,1] op_sel_hi:[1,0]
	v_pk_add_f32 v[78:79], v[78:79], v[78:79] op_sel:[0,1] op_sel_hi:[1,0]
	v_mov_b32_e32 v83, v93
	v_mov_b32_e32 v87, v94
	v_mov_b32_e32 v81, v89
	v_mov_b32_e32 v79, v92
	v_pk_add_f32 v[82:83], v[82:83], v[86:87]
	v_pk_add_f32 v[78:79], v[80:81], v[78:79]
	s_nop 0
	v_pk_add_f32 v[78:79], v[78:79], v[82:83]
	s_nop 0
	v_add_f32_e32 v78, v78, v79
	s_waitcnt lgkmcnt(0)
	s_nop 1
	v_add_f32_dpp v78, v78, v78 quad_perm:[1,0,3,2] row_mask:0xf bank_mask:0xf
	s_nop 1
	v_add_f32_dpp v78, v78, v78 quad_perm:[2,3,0,1] row_mask:0xf bank_mask:0xf
	s_nop 1
	v_add_f32_dpp v78, v78, v78 row_half_mirror row_mask:0xf bank_mask:0xf
	s_nop 1
	v_add_f32_dpp v78, v78, v78 row_mirror row_mask:0xf bank_mask:0xf
	ds_bpermute_b32 v79, v51, v78
	s_waitcnt lgkmcnt(0)
	v_add_f32_e32 v78, v78, v79
	v_mov_b32_e32 v79, v78
	s_nop 1
	v_permlane32_swap_b32_e32 v79, v78
	v_add_f32_e32 v78, v78, v79
	v_fmamk_f32 v78, v78, 0x3a800000, v55
	v_mul_f32_e32 v79, 0x4b800000, v78
	v_cmp_gt_f32_e64 s[0:1], s9, v78
	s_nop 1
	v_cndmask_b32_e64 v78, v78, v79, s[0:1]
	v_rsq_f32_e32 v78, v78
	s_nop 0
	v_mul_f32_e32 v79, 0x45800000, v78
	v_cndmask_b32_e64 v78, v78, v79, s[0:1]
	v_pk_mul_f32 v[130:131], v[130:131], v[78:79] op_sel_hi:[1,0]
	v_pk_mul_f32 v[128:129], v[128:129], v[78:79] op_sel_hi:[1,0]
	v_pk_mul_f32 v[130:131], v[98:99], v[130:131]
	v_pk_mul_f32 v[128:129], v[96:97], v[128:129]
	v_pk_fma_f32 v[130:131], v[10:11], v[130:131], v[2:3]
	v_pk_fma_f32 v[128:129], v[8:9], v[128:129], v[0:1]
	v_pk_mul_f32 v[134:135], v[134:135], v[78:79] op_sel_hi:[1,0]
	v_cvt_pk_bf16_f32 v128, v128, v129
	v_cvt_pk_bf16_f32 v129, v130, v131
	global_store_dwordx2 v[76:77], v[128:129], off
	v_pk_mul_f32 v[132:133], v[132:133], v[78:79] op_sel_hi:[1,0]
	v_pk_mul_f32 v[130:131], v[102:103], v[134:135]
	v_pk_mul_f32 v[128:129], v[100:101], v[132:133]
	v_pk_fma_f32 v[130:131], v[14:15], v[130:131], v[6:7]
	v_pk_fma_f32 v[128:129], v[12:13], v[128:129], v[4:5]
	v_pk_mul_f32 v[132:133], v[138:139], v[78:79] op_sel_hi:[1,0]
	v_cvt_pk_bf16_f32 v128, v128, v129
	v_cvt_pk_bf16_f32 v129, v130, v131
	global_store_dwordx2 v[76:77], v[128:129], off offset:512
	v_pk_mul_f32 v[134:135], v[136:137], v[78:79] op_sel_hi:[1,0]
	v_pk_mul_f32 v[130:131], v[106:107], v[132:133]
	v_pk_mul_f32 v[128:129], v[104:105], v[134:135]
	v_pk_fma_f32 v[130:131], v[26:27], v[130:131], v[18:19]
	v_pk_fma_f32 v[128:129], v[24:25], v[128:129], v[16:17]
	v_pk_mul_f32 v[132:133], v[142:143], v[78:79] op_sel_hi:[1,0]
	v_cvt_pk_bf16_f32 v128, v128, v129
	v_cvt_pk_bf16_f32 v129, v130, v131
	global_store_dwordx2 v[76:77], v[128:129], off offset:1024
	v_pk_mul_f32 v[134:135], v[140:141], v[78:79] op_sel_hi:[1,0]
	v_pk_mul_f32 v[130:131], v[110:111], v[132:133]
	v_pk_mul_f32 v[128:129], v[108:109], v[134:135]
	v_pk_fma_f32 v[130:131], v[30:31], v[130:131], v[22:23]
	v_pk_fma_f32 v[128:129], v[28:29], v[128:129], v[20:21]
	s_nop 0
	v_cvt_pk_bf16_f32 v128, v128, v129
	v_cvt_pk_bf16_f32 v129, v130, v131
	global_store_dwordx2 v[76:77], v[128:129], off offset:1536
	s_waitcnt vmcnt(28)
	v_lshl_add_u64 v[76:77], v[42:43], 0, s[6:7]
	v_add_co_u32_e64 v76, s[0:1], s10, v76
	s_add_u32 s6, s6, 0x800
	s_nop 0
	v_addc_co_u32_e64 v77, s[0:1], 0, v77, s[0:1]
	s_addc_u32 s7, s7, 0
	v_pk_mul_f32 v[78:79], v[146:147], v[146:147]
	v_pk_mul_f32 v[80:81], v[144:145], v[144:145]
	v_pk_mul_f32 v[82:83], v[150:151], v[150:151]
	v_pk_mul_f32 v[84:85], v[148:149], v[148:149]
	v_pk_mov_b32 v[90:91], v[80:81], v[78:79] op_sel:[1,0]
	v_mov_b32_e32 v81, v79
	v_pk_mov_b32 v[78:79], v[84:85], v[82:83] op_sel:[1,0]
	v_mov_b32_e32 v85, v83
	v_mul_f32_e32 v89, v156, v156
	v_mul_f32_e32 v86, v153, v153
	v_mul_f32_e32 v88, v155, v155
	v_pk_add_f32 v[80:81], v[90:91], v[80:81]
	v_pk_add_f32 v[78:79], v[78:79], v[84:85]
	v_mul_f32_e32 v92, v157, v157
	v_mul_f32_e32 v93, v158, v158
	v_mul_f32_e32 v94, v159, v159
	v_pk_fma_f32 v[82:83], v[152:153], v[152:153], v[86:87] op_sel_hi:[1,1,0]
	v_pk_fma_f32 v[86:87], v[154:155], v[154:155], v[88:89] op_sel_hi:[1,1,0]
	v_pk_add_f32 v[80:81], v[80:81], v[80:81] op_sel:[0,1] op_sel_hi:[1,0]
	v_pk_add_f32 v[78:79], v[78:79], v[78:79] op_sel:[0,1] op_sel_hi:[1,0]
	v_mov_b32_e32 v83, v93
	v_mov_b32_e32 v87, v94
	v_mov_b32_e32 v81, v89
	v_mov_b32_e32 v79, v92
	v_pk_add_f32 v[82:83], v[82:83], v[86:87]
	v_pk_add_f32 v[78:79], v[80:81], v[78:79]
	s_nop 0
	v_pk_add_f32 v[78:79], v[78:79], v[82:83]
	s_nop 0
	v_add_f32_e32 v78, v78, v79
	s_waitcnt lgkmcnt(0)
	s_nop 1
	v_add_f32_dpp v78, v78, v78 quad_perm:[1,0,3,2] row_mask:0xf bank_mask:0xf
	s_nop 1
	v_add_f32_dpp v78, v78, v78 quad_perm:[2,3,0,1] row_mask:0xf bank_mask:0xf
	s_nop 1
	v_add_f32_dpp v78, v78, v78 row_half_mirror row_mask:0xf bank_mask:0xf
	s_nop 1
	v_add_f32_dpp v78, v78, v78 row_mirror row_mask:0xf bank_mask:0xf
	ds_bpermute_b32 v79, v51, v78
	s_waitcnt lgkmcnt(0)
	v_add_f32_e32 v78, v78, v79
	v_mov_b32_e32 v79, v78
	s_nop 1
	v_permlane32_swap_b32_e32 v79, v78
	v_add_f32_e32 v78, v78, v79
	v_fmamk_f32 v78, v78, 0x3a800000, v55
	v_mul_f32_e32 v79, 0x4b800000, v78
	v_cmp_gt_f32_e64 s[0:1], s9, v78
	s_nop 1
	v_cndmask_b32_e64 v78, v78, v79, s[0:1]
	v_rsq_f32_e32 v78, v78
	s_nop 0
	v_mul_f32_e32 v79, 0x45800000, v78
	v_cndmask_b32_e64 v78, v78, v79, s[0:1]
	v_pk_mul_f32 v[146:147], v[146:147], v[78:79] op_sel_hi:[1,0]
	v_pk_mul_f32 v[144:145], v[144:145], v[78:79] op_sel_hi:[1,0]
	v_pk_mul_f32 v[146:147], v[98:99], v[146:147]
	v_pk_mul_f32 v[144:145], v[96:97], v[144:145]
	v_pk_fma_f32 v[146:147], v[10:11], v[146:147], v[2:3]
	v_pk_fma_f32 v[144:145], v[8:9], v[144:145], v[0:1]
	v_pk_mul_f32 v[150:151], v[150:151], v[78:79] op_sel_hi:[1,0]
	v_cvt_pk_bf16_f32 v144, v144, v145
	v_cvt_pk_bf16_f32 v145, v146, v147
	global_store_dwordx2 v[76:77], v[144:145], off
	v_pk_mul_f32 v[148:149], v[148:149], v[78:79] op_sel_hi:[1,0]
	v_pk_mul_f32 v[146:147], v[102:103], v[150:151]
	v_pk_mul_f32 v[144:145], v[100:101], v[148:149]
	v_pk_fma_f32 v[146:147], v[14:15], v[146:147], v[6:7]
	v_pk_fma_f32 v[144:145], v[12:13], v[144:145], v[4:5]
	v_pk_mul_f32 v[148:149], v[154:155], v[78:79] op_sel_hi:[1,0]
	v_cvt_pk_bf16_f32 v144, v144, v145
	v_cvt_pk_bf16_f32 v145, v146, v147
	global_store_dwordx2 v[76:77], v[144:145], off offset:512
	v_pk_mul_f32 v[150:151], v[152:153], v[78:79] op_sel_hi:[1,0]
	v_pk_mul_f32 v[146:147], v[106:107], v[148:149]
	v_pk_mul_f32 v[144:145], v[104:105], v[150:151]
	v_pk_fma_f32 v[146:147], v[26:27], v[146:147], v[18:19]
	v_pk_fma_f32 v[144:145], v[24:25], v[144:145], v[16:17]
	v_pk_mul_f32 v[148:149], v[158:159], v[78:79] op_sel_hi:[1,0]
	v_cvt_pk_bf16_f32 v144, v144, v145
	v_cvt_pk_bf16_f32 v145, v146, v147
	global_store_dwordx2 v[76:77], v[144:145], off offset:1024
	v_pk_mul_f32 v[150:151], v[156:157], v[78:79] op_sel_hi:[1,0]
	v_pk_mul_f32 v[146:147], v[110:111], v[148:149]
	v_pk_mul_f32 v[144:145], v[108:109], v[150:151]
	v_pk_fma_f32 v[146:147], v[30:31], v[146:147], v[22:23]
	v_pk_fma_f32 v[144:145], v[28:29], v[144:145], v[20:21]
	s_nop 0
	v_cvt_pk_bf16_f32 v144, v144, v145
	v_cvt_pk_bf16_f32 v145, v146, v147
	global_store_dwordx2 v[76:77], v[144:145], off offset:1536
	s_waitcnt vmcnt(28)
	v_lshl_add_u64 v[76:77], v[42:43], 0, s[6:7]
	v_add_co_u32_e64 v76, s[0:1], s10, v76
	s_add_u32 s6, s6, 0x800
	s_nop 0
	v_addc_co_u32_e64 v77, s[0:1], 0, v77, s[0:1]
	s_addc_u32 s7, s7, 0
	v_pk_mul_f32 v[78:79], v[162:163], v[162:163]
	v_pk_mul_f32 v[80:81], v[160:161], v[160:161]
	v_pk_mul_f32 v[82:83], v[166:167], v[166:167]
	v_pk_mul_f32 v[84:85], v[164:165], v[164:165]
	v_pk_mov_b32 v[90:91], v[80:81], v[78:79] op_sel:[1,0]
	v_mov_b32_e32 v81, v79
	v_pk_mov_b32 v[78:79], v[84:85], v[82:83] op_sel:[1,0]
	v_mov_b32_e32 v85, v83
	v_mul_f32_e32 v89, v172, v172
	v_mul_f32_e32 v86, v169, v169
	v_mul_f32_e32 v88, v171, v171
	v_pk_add_f32 v[80:81], v[90:91], v[80:81]
	v_pk_add_f32 v[78:79], v[78:79], v[84:85]
	v_mul_f32_e32 v92, v173, v173
	v_mul_f32_e32 v93, v174, v174
	v_mul_f32_e32 v94, v175, v175
	v_pk_fma_f32 v[82:83], v[168:169], v[168:169], v[86:87] op_sel_hi:[1,1,0]
	v_pk_fma_f32 v[86:87], v[170:171], v[170:171], v[88:89] op_sel_hi:[1,1,0]
	v_pk_add_f32 v[80:81], v[80:81], v[80:81] op_sel:[0,1] op_sel_hi:[1,0]
	v_pk_add_f32 v[78:79], v[78:79], v[78:79] op_sel:[0,1] op_sel_hi:[1,0]
	v_mov_b32_e32 v83, v93
	v_mov_b32_e32 v87, v94
	v_mov_b32_e32 v81, v89
	v_mov_b32_e32 v79, v92
	v_pk_add_f32 v[82:83], v[82:83], v[86:87]
	v_pk_add_f32 v[78:79], v[80:81], v[78:79]
	s_nop 0
	v_pk_add_f32 v[78:79], v[78:79], v[82:83]
	s_nop 0
	v_add_f32_e32 v78, v78, v79
	s_waitcnt lgkmcnt(0)
	s_nop 1
	v_add_f32_dpp v78, v78, v78 quad_perm:[1,0,3,2] row_mask:0xf bank_mask:0xf
	s_nop 1
	v_add_f32_dpp v78, v78, v78 quad_perm:[2,3,0,1] row_mask:0xf bank_mask:0xf
	s_nop 1
	v_add_f32_dpp v78, v78, v78 row_half_mirror row_mask:0xf bank_mask:0xf
	s_nop 1
	v_add_f32_dpp v78, v78, v78 row_mirror row_mask:0xf bank_mask:0xf
	ds_bpermute_b32 v79, v51, v78
	s_waitcnt lgkmcnt(0)
	v_add_f32_e32 v78, v78, v79
	v_mov_b32_e32 v79, v78
	s_nop 1
	v_permlane32_swap_b32_e32 v79, v78
	v_add_f32_e32 v78, v78, v79
	v_fmamk_f32 v78, v78, 0x3a800000, v55
	v_mul_f32_e32 v79, 0x4b800000, v78
	v_cmp_gt_f32_e64 s[0:1], s9, v78
	s_nop 1
	v_cndmask_b32_e64 v78, v78, v79, s[0:1]
	v_rsq_f32_e32 v78, v78
	s_nop 0
	v_mul_f32_e32 v79, 0x45800000, v78
	v_cndmask_b32_e64 v78, v78, v79, s[0:1]
	v_pk_mul_f32 v[162:163], v[162:163], v[78:79] op_sel_hi:[1,0]
	v_pk_mul_f32 v[160:161], v[160:161], v[78:79] op_sel_hi:[1,0]
	v_pk_mul_f32 v[162:163], v[98:99], v[162:163]
	v_pk_mul_f32 v[160:161], v[96:97], v[160:161]
	v_pk_fma_f32 v[162:163], v[10:11], v[162:163], v[2:3]
	v_pk_fma_f32 v[160:161], v[8:9], v[160:161], v[0:1]
	v_pk_mul_f32 v[166:167], v[166:167], v[78:79] op_sel_hi:[1,0]
	v_cvt_pk_bf16_f32 v160, v160, v161
	v_cvt_pk_bf16_f32 v161, v162, v163
	global_store_dwordx2 v[76:77], v[160:161], off
	v_pk_mul_f32 v[164:165], v[164:165], v[78:79] op_sel_hi:[1,0]
	v_pk_mul_f32 v[162:163], v[102:103], v[166:167]
	v_pk_mul_f32 v[160:161], v[100:101], v[164:165]
	v_pk_fma_f32 v[162:163], v[14:15], v[162:163], v[6:7]
	v_pk_fma_f32 v[160:161], v[12:13], v[160:161], v[4:5]
	v_pk_mul_f32 v[164:165], v[170:171], v[78:79] op_sel_hi:[1,0]
	v_cvt_pk_bf16_f32 v160, v160, v161
	v_cvt_pk_bf16_f32 v161, v162, v163
	global_store_dwordx2 v[76:77], v[160:161], off offset:512
	v_pk_mul_f32 v[166:167], v[168:169], v[78:79] op_sel_hi:[1,0]
	v_pk_mul_f32 v[162:163], v[106:107], v[164:165]
	v_pk_mul_f32 v[160:161], v[104:105], v[166:167]
	v_pk_fma_f32 v[162:163], v[26:27], v[162:163], v[18:19]
	v_pk_fma_f32 v[160:161], v[24:25], v[160:161], v[16:17]
	v_pk_mul_f32 v[164:165], v[174:175], v[78:79] op_sel_hi:[1,0]
	v_cvt_pk_bf16_f32 v160, v160, v161
	v_cvt_pk_bf16_f32 v161, v162, v163
	global_store_dwordx2 v[76:77], v[160:161], off offset:1024
	v_pk_mul_f32 v[166:167], v[172:173], v[78:79] op_sel_hi:[1,0]
	v_pk_mul_f32 v[162:163], v[110:111], v[164:165]
	v_pk_mul_f32 v[160:161], v[108:109], v[166:167]
	v_pk_fma_f32 v[162:163], v[30:31], v[162:163], v[22:23]
	v_pk_fma_f32 v[160:161], v[28:29], v[160:161], v[20:21]
	s_nop 0
	v_cvt_pk_bf16_f32 v160, v160, v161
	v_cvt_pk_bf16_f32 v161, v162, v163
	global_store_dwordx2 v[76:77], v[160:161], off offset:1536
	s_waitcnt vmcnt(28)
	v_lshl_add_u64 v[76:77], v[42:43], 0, s[6:7]
	v_add_co_u32_e64 v76, s[0:1], s10, v76
	s_add_u32 s6, s6, 0x800
	s_nop 0
	v_addc_co_u32_e64 v77, s[0:1], 0, v77, s[0:1]
	s_addc_u32 s7, s7, 0
	v_pk_mul_f32 v[78:79], v[178:179], v[178:179]
	v_pk_mul_f32 v[80:81], v[176:177], v[176:177]
	v_pk_mul_f32 v[82:83], v[182:183], v[182:183]
	v_pk_mul_f32 v[84:85], v[180:181], v[180:181]
	v_pk_mov_b32 v[90:91], v[80:81], v[78:79] op_sel:[1,0]
	v_mov_b32_e32 v81, v79
	v_pk_mov_b32 v[78:79], v[84:85], v[82:83] op_sel:[1,0]
	v_mov_b32_e32 v85, v83
	v_mul_f32_e32 v89, v188, v188
	v_mul_f32_e32 v86, v185, v185
	v_mul_f32_e32 v88, v187, v187
	v_pk_add_f32 v[80:81], v[90:91], v[80:81]
	v_pk_add_f32 v[78:79], v[78:79], v[84:85]
	v_mul_f32_e32 v92, v189, v189
	v_mul_f32_e32 v93, v190, v190
	v_mul_f32_e32 v94, v191, v191
	v_pk_fma_f32 v[82:83], v[184:185], v[184:185], v[86:87] op_sel_hi:[1,1,0]
	v_pk_fma_f32 v[86:87], v[186:187], v[186:187], v[88:89] op_sel_hi:[1,1,0]
	v_pk_add_f32 v[80:81], v[80:81], v[80:81] op_sel:[0,1] op_sel_hi:[1,0]
	v_pk_add_f32 v[78:79], v[78:79], v[78:79] op_sel:[0,1] op_sel_hi:[1,0]
	v_mov_b32_e32 v83, v93
	v_mov_b32_e32 v87, v94
	v_mov_b32_e32 v81, v89
	v_mov_b32_e32 v79, v92
	v_pk_add_f32 v[82:83], v[82:83], v[86:87]
	v_pk_add_f32 v[78:79], v[80:81], v[78:79]
	s_nop 0
	v_pk_add_f32 v[78:79], v[78:79], v[82:83]
	s_nop 0
	v_add_f32_e32 v78, v78, v79
	s_waitcnt lgkmcnt(0)
	s_nop 1
	v_add_f32_dpp v78, v78, v78 quad_perm:[1,0,3,2] row_mask:0xf bank_mask:0xf
	s_nop 1
	v_add_f32_dpp v78, v78, v78 quad_perm:[2,3,0,1] row_mask:0xf bank_mask:0xf
	s_nop 1
	v_add_f32_dpp v78, v78, v78 row_half_mirror row_mask:0xf bank_mask:0xf
	s_nop 1
	v_add_f32_dpp v78, v78, v78 row_mirror row_mask:0xf bank_mask:0xf
	ds_bpermute_b32 v79, v51, v78
	s_waitcnt lgkmcnt(0)
	v_add_f32_e32 v78, v78, v79
	v_mov_b32_e32 v79, v78
	s_nop 1
	v_permlane32_swap_b32_e32 v79, v78
	v_add_f32_e32 v78, v78, v79
	v_fmamk_f32 v78, v78, 0x3a800000, v55
	v_mul_f32_e32 v79, 0x4b800000, v78
	v_cmp_gt_f32_e64 s[0:1], s9, v78
	s_nop 1
	v_cndmask_b32_e64 v78, v78, v79, s[0:1]
	v_rsq_f32_e32 v78, v78
	s_nop 0
	v_mul_f32_e32 v79, 0x45800000, v78
	v_cndmask_b32_e64 v78, v78, v79, s[0:1]
	v_pk_mul_f32 v[178:179], v[178:179], v[78:79] op_sel_hi:[1,0]
	v_pk_mul_f32 v[176:177], v[176:177], v[78:79] op_sel_hi:[1,0]
	v_pk_mul_f32 v[178:179], v[98:99], v[178:179]
	v_pk_mul_f32 v[176:177], v[96:97], v[176:177]
	v_pk_fma_f32 v[178:179], v[10:11], v[178:179], v[2:3]
	v_pk_fma_f32 v[176:177], v[8:9], v[176:177], v[0:1]
	v_pk_mul_f32 v[182:183], v[182:183], v[78:79] op_sel_hi:[1,0]
	v_cvt_pk_bf16_f32 v176, v176, v177
	v_cvt_pk_bf16_f32 v177, v178, v179
	global_store_dwordx2 v[76:77], v[176:177], off
	v_pk_mul_f32 v[180:181], v[180:181], v[78:79] op_sel_hi:[1,0]
	v_pk_mul_f32 v[178:179], v[102:103], v[182:183]
	v_pk_mul_f32 v[176:177], v[100:101], v[180:181]
	v_pk_fma_f32 v[178:179], v[14:15], v[178:179], v[6:7]
	v_pk_fma_f32 v[176:177], v[12:13], v[176:177], v[4:5]
	v_pk_mul_f32 v[180:181], v[186:187], v[78:79] op_sel_hi:[1,0]
	v_cvt_pk_bf16_f32 v176, v176, v177
	v_cvt_pk_bf16_f32 v177, v178, v179
	global_store_dwordx2 v[76:77], v[176:177], off offset:512
	v_pk_mul_f32 v[182:183], v[184:185], v[78:79] op_sel_hi:[1,0]
	v_pk_mul_f32 v[178:179], v[106:107], v[180:181]
	v_pk_mul_f32 v[176:177], v[104:105], v[182:183]
	v_pk_fma_f32 v[178:179], v[26:27], v[178:179], v[18:19]
	v_pk_fma_f32 v[176:177], v[24:25], v[176:177], v[16:17]
	v_pk_mul_f32 v[180:181], v[190:191], v[78:79] op_sel_hi:[1,0]
	v_cvt_pk_bf16_f32 v176, v176, v177
	v_cvt_pk_bf16_f32 v177, v178, v179
	global_store_dwordx2 v[76:77], v[176:177], off offset:1024
	v_pk_mul_f32 v[182:183], v[188:189], v[78:79] op_sel_hi:[1,0]
	v_pk_mul_f32 v[178:179], v[110:111], v[180:181]
	v_pk_mul_f32 v[176:177], v[108:109], v[182:183]
	v_pk_fma_f32 v[178:179], v[30:31], v[178:179], v[22:23]
	v_pk_fma_f32 v[176:177], v[28:29], v[176:177], v[20:21]
	s_nop 0
	v_cvt_pk_bf16_f32 v176, v176, v177
	v_cvt_pk_bf16_f32 v177, v178, v179
	global_store_dwordx2 v[76:77], v[176:177], off offset:1536
	s_waitcnt vmcnt(28)
	v_lshl_add_u64 v[76:77], v[42:43], 0, s[6:7]
	v_add_co_u32_e64 v76, s[0:1], s10, v76
	s_add_u32 s6, s6, 0x800
	s_nop 0
	v_addc_co_u32_e64 v77, s[0:1], 0, v77, s[0:1]
	s_addc_u32 s7, s7, 0
	v_pk_mul_f32 v[78:79], v[212:213], v[212:213]
	v_pk_mul_f32 v[80:81], v[210:211], v[210:211]
	v_pk_mul_f32 v[82:83], v[216:217], v[216:217]
	v_pk_mul_f32 v[84:85], v[214:215], v[214:215]
	v_pk_mov_b32 v[90:91], v[80:81], v[78:79] op_sel:[1,0]
	v_mov_b32_e32 v81, v79
	v_pk_mov_b32 v[78:79], v[84:85], v[82:83] op_sel:[1,0]
	v_mov_b32_e32 v85, v83
	v_mul_f32_e32 v89, v222, v222
	v_mul_f32_e32 v86, v219, v219
	v_mul_f32_e32 v88, v221, v221
	v_pk_add_f32 v[80:81], v[90:91], v[80:81]
	v_pk_add_f32 v[78:79], v[78:79], v[84:85]
	v_mul_f32_e32 v92, v223, v223
	v_mul_f32_e32 v93, v224, v224
	v_mul_f32_e32 v94, v225, v225
	v_pk_fma_f32 v[82:83], v[218:219], v[218:219], v[86:87] op_sel_hi:[1,1,0]
	v_pk_fma_f32 v[86:87], v[220:221], v[220:221], v[88:89] op_sel_hi:[1,1,0]
	v_pk_add_f32 v[80:81], v[80:81], v[80:81] op_sel:[0,1] op_sel_hi:[1,0]
	v_pk_add_f32 v[78:79], v[78:79], v[78:79] op_sel:[0,1] op_sel_hi:[1,0]
	v_mov_b32_e32 v83, v93
	v_mov_b32_e32 v87, v94
	v_mov_b32_e32 v81, v89
	v_mov_b32_e32 v79, v92
	v_pk_add_f32 v[82:83], v[82:83], v[86:87]
	v_pk_add_f32 v[78:79], v[80:81], v[78:79]
	s_nop 0
	v_pk_add_f32 v[78:79], v[78:79], v[82:83]
	s_nop 0
	v_add_f32_e32 v78, v78, v79
	s_waitcnt lgkmcnt(0)
	s_nop 1
	v_add_f32_dpp v78, v78, v78 quad_perm:[1,0,3,2] row_mask:0xf bank_mask:0xf
	s_nop 1
	v_add_f32_dpp v78, v78, v78 quad_perm:[2,3,0,1] row_mask:0xf bank_mask:0xf
	s_nop 1
	v_add_f32_dpp v78, v78, v78 row_half_mirror row_mask:0xf bank_mask:0xf
	s_nop 1
	v_add_f32_dpp v78, v78, v78 row_mirror row_mask:0xf bank_mask:0xf
	ds_bpermute_b32 v79, v51, v78
	s_waitcnt lgkmcnt(0)
	v_add_f32_e32 v78, v78, v79
	v_mov_b32_e32 v79, v78
	s_nop 1
	v_permlane32_swap_b32_e32 v79, v78
	v_add_f32_e32 v78, v78, v79
	v_fmamk_f32 v78, v78, 0x3a800000, v55
	v_mul_f32_e32 v79, 0x4b800000, v78
	v_cmp_gt_f32_e64 s[0:1], s9, v78
	s_nop 1
	v_cndmask_b32_e64 v78, v78, v79, s[0:1]
	v_rsq_f32_e32 v78, v78
	s_nop 0
	v_mul_f32_e32 v79, 0x45800000, v78
	v_cndmask_b32_e64 v78, v78, v79, s[0:1]
	v_pk_mul_f32 v[212:213], v[212:213], v[78:79] op_sel_hi:[1,0]
	v_pk_mul_f32 v[210:211], v[210:211], v[78:79] op_sel_hi:[1,0]
	v_pk_mul_f32 v[212:213], v[98:99], v[212:213]
	v_pk_mul_f32 v[210:211], v[96:97], v[210:211]
	v_pk_fma_f32 v[212:213], v[10:11], v[212:213], v[2:3]
	v_pk_fma_f32 v[210:211], v[8:9], v[210:211], v[0:1]
	v_pk_mul_f32 v[216:217], v[216:217], v[78:79] op_sel_hi:[1,0]
	v_cvt_pk_bf16_f32 v210, v210, v211
	v_cvt_pk_bf16_f32 v211, v212, v213
	global_store_dwordx2 v[76:77], v[210:211], off
	v_pk_mul_f32 v[214:215], v[214:215], v[78:79] op_sel_hi:[1,0]
	v_pk_mul_f32 v[212:213], v[102:103], v[216:217]
	v_pk_mul_f32 v[210:211], v[100:101], v[214:215]
	v_pk_fma_f32 v[212:213], v[14:15], v[212:213], v[6:7]
	v_pk_fma_f32 v[210:211], v[12:13], v[210:211], v[4:5]
	v_pk_mul_f32 v[214:215], v[220:221], v[78:79] op_sel_hi:[1,0]
	v_cvt_pk_bf16_f32 v210, v210, v211
	v_cvt_pk_bf16_f32 v211, v212, v213
	global_store_dwordx2 v[76:77], v[210:211], off offset:512
	v_pk_mul_f32 v[216:217], v[218:219], v[78:79] op_sel_hi:[1,0]
	v_pk_mul_f32 v[212:213], v[106:107], v[214:215]
	v_pk_mul_f32 v[210:211], v[104:105], v[216:217]
	v_pk_fma_f32 v[212:213], v[26:27], v[212:213], v[18:19]
	v_pk_fma_f32 v[210:211], v[24:25], v[210:211], v[16:17]
	v_pk_mul_f32 v[214:215], v[224:225], v[78:79] op_sel_hi:[1,0]
	v_cvt_pk_bf16_f32 v210, v210, v211
	v_cvt_pk_bf16_f32 v211, v212, v213
	global_store_dwordx2 v[76:77], v[210:211], off offset:1024
	v_pk_mul_f32 v[216:217], v[222:223], v[78:79] op_sel_hi:[1,0]
	v_pk_mul_f32 v[212:213], v[110:111], v[214:215]
	v_pk_mul_f32 v[210:211], v[108:109], v[216:217]
	v_pk_fma_f32 v[212:213], v[30:31], v[212:213], v[22:23]
	v_pk_fma_f32 v[210:211], v[28:29], v[210:211], v[20:21]
	s_nop 0
	v_cvt_pk_bf16_f32 v210, v210, v211
	v_cvt_pk_bf16_f32 v211, v212, v213
	global_store_dwordx2 v[76:77], v[210:211], off offset:1536
	s_waitcnt vmcnt(28)
	v_lshl_add_u64 v[76:77], v[42:43], 0, s[6:7]
	v_add_co_u32_e64 v76, s[0:1], s10, v76
	s_add_u32 s6, s6, 0x800
	s_nop 0
	v_addc_co_u32_e64 v77, s[0:1], 0, v77, s[0:1]
	s_addc_u32 s7, s7, 0
	v_pk_mul_f32 v[78:79], v[228:229], v[228:229]
	v_pk_mul_f32 v[80:81], v[226:227], v[226:227]
	v_pk_mul_f32 v[82:83], v[232:233], v[232:233]
	v_pk_mul_f32 v[84:85], v[230:231], v[230:231]
	v_pk_mov_b32 v[90:91], v[80:81], v[78:79] op_sel:[1,0]
	v_mov_b32_e32 v81, v79
	v_pk_mov_b32 v[78:79], v[84:85], v[82:83] op_sel:[1,0]
	v_mov_b32_e32 v85, v83
	v_mul_f32_e32 v89, v238, v238
	v_mul_f32_e32 v86, v235, v235
	v_mul_f32_e32 v88, v237, v237
	v_pk_add_f32 v[80:81], v[90:91], v[80:81]
	v_pk_add_f32 v[78:79], v[78:79], v[84:85]
	v_mul_f32_e32 v92, v239, v239
	v_mul_f32_e32 v93, v240, v240
	v_mul_f32_e32 v94, v241, v241
	v_pk_fma_f32 v[82:83], v[234:235], v[234:235], v[86:87] op_sel_hi:[1,1,0]
	v_pk_fma_f32 v[86:87], v[236:237], v[236:237], v[88:89] op_sel_hi:[1,1,0]
	v_pk_add_f32 v[80:81], v[80:81], v[80:81] op_sel:[0,1] op_sel_hi:[1,0]
	v_pk_add_f32 v[78:79], v[78:79], v[78:79] op_sel:[0,1] op_sel_hi:[1,0]
	v_mov_b32_e32 v83, v93
	v_mov_b32_e32 v87, v94
	v_mov_b32_e32 v81, v89
	v_mov_b32_e32 v79, v92
	v_pk_add_f32 v[82:83], v[82:83], v[86:87]
	v_pk_add_f32 v[78:79], v[80:81], v[78:79]
	s_nop 0
	v_pk_add_f32 v[78:79], v[78:79], v[82:83]
	s_nop 0
	v_add_f32_e32 v78, v78, v79
	s_waitcnt lgkmcnt(0)
	s_nop 1
	v_add_f32_dpp v78, v78, v78 quad_perm:[1,0,3,2] row_mask:0xf bank_mask:0xf
	s_nop 1
	v_add_f32_dpp v78, v78, v78 quad_perm:[2,3,0,1] row_mask:0xf bank_mask:0xf
	s_nop 1
	v_add_f32_dpp v78, v78, v78 row_half_mirror row_mask:0xf bank_mask:0xf
	s_nop 1
	v_add_f32_dpp v78, v78, v78 row_mirror row_mask:0xf bank_mask:0xf
	ds_bpermute_b32 v79, v51, v78
	s_waitcnt lgkmcnt(0)
	v_add_f32_e32 v78, v78, v79
	v_mov_b32_e32 v79, v78
	s_nop 1
	v_permlane32_swap_b32_e32 v79, v78
	v_add_f32_e32 v78, v78, v79
	v_fmamk_f32 v78, v78, 0x3a800000, v55
	v_mul_f32_e32 v79, 0x4b800000, v78
	v_cmp_gt_f32_e64 s[0:1], s9, v78
	s_nop 1
	v_cndmask_b32_e64 v78, v78, v79, s[0:1]
	v_rsq_f32_e32 v78, v78
	s_nop 0
	v_mul_f32_e32 v79, 0x45800000, v78
	v_cndmask_b32_e64 v78, v78, v79, s[0:1]
	v_pk_mul_f32 v[228:229], v[228:229], v[78:79] op_sel_hi:[1,0]
	v_pk_mul_f32 v[226:227], v[226:227], v[78:79] op_sel_hi:[1,0]
	v_pk_mul_f32 v[228:229], v[98:99], v[228:229]
	v_pk_mul_f32 v[226:227], v[96:97], v[226:227]
	v_pk_fma_f32 v[228:229], v[10:11], v[228:229], v[2:3]
	v_pk_fma_f32 v[226:227], v[8:9], v[226:227], v[0:1]
	v_pk_mul_f32 v[232:233], v[232:233], v[78:79] op_sel_hi:[1,0]
	v_cvt_pk_bf16_f32 v226, v226, v227
	v_cvt_pk_bf16_f32 v227, v228, v229
	global_store_dwordx2 v[76:77], v[226:227], off
	v_pk_mul_f32 v[230:231], v[230:231], v[78:79] op_sel_hi:[1,0]
	v_pk_mul_f32 v[228:229], v[102:103], v[232:233]
	v_pk_mul_f32 v[226:227], v[100:101], v[230:231]
	v_pk_fma_f32 v[228:229], v[14:15], v[228:229], v[6:7]
	v_pk_fma_f32 v[226:227], v[12:13], v[226:227], v[4:5]
	v_pk_mul_f32 v[230:231], v[236:237], v[78:79] op_sel_hi:[1,0]
	v_cvt_pk_bf16_f32 v226, v226, v227
	v_cvt_pk_bf16_f32 v227, v228, v229
	global_store_dwordx2 v[76:77], v[226:227], off offset:512
	v_pk_mul_f32 v[232:233], v[234:235], v[78:79] op_sel_hi:[1,0]
	v_pk_mul_f32 v[228:229], v[106:107], v[230:231]
	v_pk_mul_f32 v[226:227], v[104:105], v[232:233]
	v_pk_fma_f32 v[228:229], v[26:27], v[228:229], v[18:19]
	v_pk_fma_f32 v[226:227], v[24:25], v[226:227], v[16:17]
	v_pk_mul_f32 v[230:231], v[240:241], v[78:79] op_sel_hi:[1,0]
	v_cvt_pk_bf16_f32 v226, v226, v227
	v_cvt_pk_bf16_f32 v227, v228, v229
	global_store_dwordx2 v[76:77], v[226:227], off offset:1024
	v_pk_mul_f32 v[232:233], v[238:239], v[78:79] op_sel_hi:[1,0]
	v_pk_mul_f32 v[228:229], v[110:111], v[230:231]
	v_pk_mul_f32 v[226:227], v[108:109], v[232:233]
	v_pk_fma_f32 v[228:229], v[30:31], v[228:229], v[22:23]
	v_pk_fma_f32 v[226:227], v[28:29], v[226:227], v[20:21]
	s_nop 0
	v_cvt_pk_bf16_f32 v226, v226, v227
	v_cvt_pk_bf16_f32 v227, v228, v229
	global_store_dwordx2 v[76:77], v[226:227], off offset:1536
	s_waitcnt vmcnt(24)
	v_lshl_add_u64 v[76:77], v[42:43], 0, s[6:7]
	v_add_co_u32_e64 v76, s[0:1], s10, v76
	s_add_u32 s6, s6, 0x800
	s_nop 0
	v_addc_co_u32_e64 v77, s[0:1], 0, v77, s[0:1]
	s_addc_u32 s7, s7, 0
	v_pk_mul_f32 v[78:79], v[114:115], v[114:115]
	v_pk_mul_f32 v[80:81], v[112:113], v[112:113]
	v_pk_mul_f32 v[82:83], v[118:119], v[118:119]
	v_pk_mul_f32 v[84:85], v[116:117], v[116:117]
	v_pk_mov_b32 v[90:91], v[80:81], v[78:79] op_sel:[1,0]
	v_mov_b32_e32 v81, v79
	v_pk_mov_b32 v[78:79], v[84:85], v[82:83] op_sel:[1,0]
	v_mov_b32_e32 v85, v83
	v_mul_f32_e32 v89, v124, v124
	v_mul_f32_e32 v86, v121, v121
	v_mul_f32_e32 v88, v123, v123
	v_pk_add_f32 v[80:81], v[90:91], v[80:81]
	v_pk_add_f32 v[78:79], v[78:79], v[84:85]
	v_mul_f32_e32 v92, v125, v125
	v_mul_f32_e32 v93, v126, v126
	v_mul_f32_e32 v94, v127, v127
	v_pk_fma_f32 v[82:83], v[120:121], v[120:121], v[86:87] op_sel_hi:[1,1,0]
	v_pk_fma_f32 v[86:87], v[122:123], v[122:123], v[88:89] op_sel_hi:[1,1,0]
	v_pk_add_f32 v[80:81], v[80:81], v[80:81] op_sel:[0,1] op_sel_hi:[1,0]
	v_pk_add_f32 v[78:79], v[78:79], v[78:79] op_sel:[0,1] op_sel_hi:[1,0]
	v_mov_b32_e32 v83, v93
	v_mov_b32_e32 v87, v94
	v_mov_b32_e32 v81, v89
	v_mov_b32_e32 v79, v92
	v_pk_add_f32 v[82:83], v[82:83], v[86:87]
	v_pk_add_f32 v[78:79], v[80:81], v[78:79]
	s_nop 0
	v_pk_add_f32 v[78:79], v[78:79], v[82:83]
	s_nop 0
	v_add_f32_e32 v78, v78, v79
	s_waitcnt lgkmcnt(0)
	s_nop 1
	v_add_f32_dpp v78, v78, v78 quad_perm:[1,0,3,2] row_mask:0xf bank_mask:0xf
	s_nop 1
	v_add_f32_dpp v78, v78, v78 quad_perm:[2,3,0,1] row_mask:0xf bank_mask:0xf
	s_nop 1
	v_add_f32_dpp v78, v78, v78 row_half_mirror row_mask:0xf bank_mask:0xf
	s_nop 1
	v_add_f32_dpp v78, v78, v78 row_mirror row_mask:0xf bank_mask:0xf
	ds_bpermute_b32 v79, v51, v78
	s_waitcnt lgkmcnt(0)
	v_add_f32_e32 v78, v78, v79
	v_mov_b32_e32 v79, v78
	s_nop 1
	v_permlane32_swap_b32_e32 v79, v78
	v_add_f32_e32 v78, v78, v79
	v_fmamk_f32 v78, v78, 0x3a800000, v55
	v_mul_f32_e32 v79, 0x4b800000, v78
	v_cmp_gt_f32_e64 s[0:1], s9, v78
	s_nop 1
	v_cndmask_b32_e64 v78, v78, v79, s[0:1]
	v_rsq_f32_e32 v78, v78
	s_nop 0
	v_mul_f32_e32 v79, 0x45800000, v78
	v_cndmask_b32_e64 v78, v78, v79, s[0:1]
	v_pk_mul_f32 v[114:115], v[114:115], v[78:79] op_sel_hi:[1,0]
	v_pk_mul_f32 v[112:113], v[112:113], v[78:79] op_sel_hi:[1,0]
	v_pk_mul_f32 v[114:115], v[98:99], v[114:115]
	v_pk_mul_f32 v[112:113], v[96:97], v[112:113]
	v_pk_fma_f32 v[114:115], v[10:11], v[114:115], v[2:3]
	v_pk_fma_f32 v[112:113], v[8:9], v[112:113], v[0:1]
	v_pk_mul_f32 v[118:119], v[118:119], v[78:79] op_sel_hi:[1,0]
	v_cvt_pk_bf16_f32 v112, v112, v113
	v_cvt_pk_bf16_f32 v113, v114, v115
	global_store_dwordx2 v[76:77], v[112:113], off
	v_pk_mul_f32 v[116:117], v[116:117], v[78:79] op_sel_hi:[1,0]
	v_pk_mul_f32 v[114:115], v[102:103], v[118:119]
	v_pk_mul_f32 v[112:113], v[100:101], v[116:117]
	v_pk_fma_f32 v[114:115], v[14:15], v[114:115], v[6:7]
	v_pk_fma_f32 v[112:113], v[12:13], v[112:113], v[4:5]
	v_pk_mul_f32 v[116:117], v[122:123], v[78:79] op_sel_hi:[1,0]
	v_cvt_pk_bf16_f32 v112, v112, v113
	v_cvt_pk_bf16_f32 v113, v114, v115
	global_store_dwordx2 v[76:77], v[112:113], off offset:512
	v_pk_mul_f32 v[118:119], v[120:121], v[78:79] op_sel_hi:[1,0]
	v_pk_mul_f32 v[114:115], v[106:107], v[116:117]
	v_pk_mul_f32 v[112:113], v[104:105], v[118:119]
	v_pk_fma_f32 v[114:115], v[26:27], v[114:115], v[18:19]
	v_pk_fma_f32 v[112:113], v[24:25], v[112:113], v[16:17]
	v_pk_mul_f32 v[116:117], v[126:127], v[78:79] op_sel_hi:[1,0]
	v_cvt_pk_bf16_f32 v112, v112, v113
	v_cvt_pk_bf16_f32 v113, v114, v115
	global_store_dwordx2 v[76:77], v[112:113], off offset:1024
	v_pk_mul_f32 v[118:119], v[124:125], v[78:79] op_sel_hi:[1,0]
	v_pk_mul_f32 v[114:115], v[110:111], v[116:117]
	v_pk_mul_f32 v[112:113], v[108:109], v[118:119]
	v_pk_fma_f32 v[114:115], v[30:31], v[114:115], v[22:23]
	v_pk_fma_f32 v[112:113], v[28:29], v[112:113], v[20:21]
	s_nop 0
	v_cvt_pk_bf16_f32 v112, v112, v113
	v_cvt_pk_bf16_f32 v113, v114, v115
	global_store_dwordx2 v[76:77], v[112:113], off offset:1536
	s_add_i32 s11, s11, s92
	s_add_i32 s2, s2, s8
	s_cmpk_gt_i32 s11, 0xff
	s_cbranch_scc0 .LBB0_225
